# attention work queue: whole latent units dealt from eight per-XCD heads (120 each, stealing), half-key units from the shared head, for K/V L2 locality
# speedup vs baseline: 1.0113x; 1.0113x over previous
.LBB0_1301:
	s_barrier
	s_and_saveexec_b64 s[10:11], s[6:7]
	s_cbranch_execz .LBB0_1311
	s_andn2_b64 vcc, exec, s[20:21]
	v_mov_b32_e32 v0, -1
	s_cbranch_vccnz .LBB0_1306
	s_getreg_b32 s22, hwreg(HW_REG_XCC_ID, 0, 4)
	s_and_b32 s22, s22, 7
	s_mov_b32 s23, 0
.Lq_try:
	s_add_i32 s24, s22, s23
	s_and_b32 s24, s24, 7
	s_lshl_b32 s25, s24, 10
	s_add_i32 s25, s25, 0x2000
	v_mov_b32_e32 v0, s25
	v_mov_b32_e32 v2, 1
	global_atomic_add v2, v0, v2, s[16:17] sc0
	s_waitcnt vmcnt(0)
	v_readfirstlane_b32 s0, v2
	s_nop 3
	s_cmpk_lt_u32 s0, 0x78
	s_cbranch_scc1 .Lq_got
	s_add_i32 s23, s23, 1
	s_cmpk_lt_u32 s23, 8
	s_cbranch_scc1 .Lq_try
	v_mov_b32_e32 v2, 1
	global_atomic_add v2, v1, v2, s[16:17] sc0
	s_waitcnt vmcnt(0)
	v_readfirstlane_b32 s0, v2
	s_nop 3
	s_add_i32 s24, s0, 0x3c0
	s_cmpk_lt_u32 s0, 0x80
	s_cselect_b32 s0, s24, -1
	v_mov_b32_e32 v0, s0
	s_branch .LBB0_1306
.Lq_got:
	s_mul_i32 s24, s24, 0x78
	s_add_i32 s0, s0, s24
	v_mov_b32_e32 v0, s0
